# v54 + scan S2 row-sum reductions via v_permlane16/32_swap instead of ds_bpermute round trips
# speedup vs baseline: 1.0052x; 1.0006x over previous
.LBB0_216:
	v_add_u32_e32 v120, s96, v174
	ds_read_b128 v[124:127], v120
	ds_read_b32 v202, v198
	s_waitcnt lgkmcnt(0)
	v_sub_f32_e32 v121, v124, v202
	v_sub_f32_e32 v122, v125, v202
	v_mul_f32_e32 v121, 0x3fb8aa3b, v121
	v_mul_f32_e32 v122, 0x3fb8aa3b, v122
	v_exp_f32_e32 v219, v121
	v_exp_f32_e32 v220, v122
	ds_read_b128 v[120:123], v120 offset:64
	v_sub_f32_e32 v221, v126, v202
	v_mul_f32_e32 v221, 0x3fb8aa3b, v221
	v_sub_f32_e32 v222, v127, v202
	v_exp_f32_e32 v221, v221
	v_mul_f32_e32 v222, 0x3fb8aa3b, v222
	s_waitcnt lgkmcnt(0)
	v_sub_f32_e32 v223, v120, v202
	v_exp_f32_e32 v222, v222
	v_mul_f32_e32 v223, 0x3fb8aa3b, v223
	v_sub_f32_e32 v224, v121, v202
	v_cndmask_b32_e64 v219, v219, 0, s[18:19]
	v_exp_f32_e32 v223, v223
	v_mul_f32_e32 v224, 0x3fb8aa3b, v224
	v_sub_f32_e32 v225, v122, v202
	v_cndmask_b32_e64 v220, 0, v220, s[20:21]
	v_fma_f32 v227, v116, v219, 0
	v_exp_f32_e32 v224, v224
	v_mul_f32_e32 v225, 0x3fb8aa3b, v225
	v_sub_f32_e32 v202, v123, v202
	v_fmac_f32_e32 v227, v117, v220
	v_cndmask_b32_e64 v221, v221, 0, s[22:23]
	v_exp_f32_e32 v225, v225
	v_mul_f32_e32 v202, 0x3fb8aa3b, v202
	v_fmac_f32_e32 v227, v118, v221
	v_cndmask_b32_e64 v222, v222, 0, s[24:25]
	v_exp_f32_e32 v202, v202
	v_fmac_f32_e32 v227, v119, v222
	v_cndmask_b32_e64 v223, v223, 0, s[26:27]
	v_fmac_f32_e32 v227, v108, v223
	v_cndmask_b32_e64 v224, v224, 0, s[28:29]
	v_fmac_f32_e32 v227, v109, v224
	v_cndmask_b32_e64 v225, v225, 0, s[30:31]
	v_fmac_f32_e32 v227, v110, v225
	v_cndmask_b32_e64 v226, v202, 0, s[34:35]
	v_fmac_f32_e32 v227, v111, v226
	v_mov_b32_e32 v202, v227
	s_nop 1
	v_permlane16_swap_b32_e32 v227, v202
	v_add_f32_e32 v227, v227, v202
	v_mov_b32_e32 v228, v227
	s_nop 1
	v_permlane32_swap_b32_e32 v227, v228
	s_and_saveexec_b64 s[86:87], s[8:9]
	s_cbranch_execz .LBB0_218
	v_add_f32_e32 v202, v227, v228
	ds_write_b32 v199, v202
.LBB0_218:
	s_or_b64 exec, exec, s[86:87]
	ds_read_b32 v202, v209
	s_waitcnt lgkmcnt(0)
	v_sub_f32_e32 v227, v124, v202
	v_sub_f32_e32 v228, v125, v202
	v_mul_f32_e32 v227, 0x3fb8aa3b, v227
	v_sub_f32_e32 v229, v126, v202
	v_mul_f32_e32 v228, 0x3fb8aa3b, v228
	v_exp_f32_e32 v227, v227
	v_exp_f32_e32 v228, v228
	v_mul_f32_e32 v229, 0x3fb8aa3b, v229
	v_sub_f32_e32 v230, v127, v202
	v_exp_f32_e32 v229, v229
	v_mul_f32_e32 v230, 0x3fb8aa3b, v230
	v_sub_f32_e32 v231, v120, v202
	v_exp_f32_e32 v230, v230
	v_mul_f32_e32 v231, 0x3fb8aa3b, v231
	v_sub_f32_e32 v232, v121, v202
	v_cndmask_b32_e64 v227, v227, 0, s[36:37]
	v_exp_f32_e32 v231, v231
	v_mul_f32_e32 v232, 0x3fb8aa3b, v232
	v_sub_f32_e32 v233, v122, v202
	v_cndmask_b32_e64 v228, 0, v228, s[38:39]
	v_fma_f32 v235, v112, v227, 0
	v_exp_f32_e32 v232, v232
	v_mul_f32_e32 v233, 0x3fb8aa3b, v233
	v_sub_f32_e32 v202, v123, v202
	v_fmac_f32_e32 v235, v113, v228
	v_cndmask_b32_e64 v229, v229, 0, s[40:41]
	v_exp_f32_e32 v233, v233
	v_mul_f32_e32 v202, 0x3fb8aa3b, v202
	v_fmac_f32_e32 v235, v114, v229
	v_cndmask_b32_e64 v230, v230, 0, s[42:43]
	v_exp_f32_e32 v202, v202
	v_fmac_f32_e32 v235, v115, v230
	v_cndmask_b32_e64 v231, v231, 0, s[18:19]
	v_fmac_f32_e32 v235, v100, v231
	v_cndmask_b32_e64 v232, v232, 0, s[44:45]
	v_fmac_f32_e32 v235, v101, v232
	v_cndmask_b32_e64 v233, v233, 0, s[46:47]
	v_fmac_f32_e32 v235, v102, v233
	v_cndmask_b32_e64 v234, v202, 0, s[48:49]
	v_fmac_f32_e32 v235, v103, v234
	v_mov_b32_e32 v202, v235
	s_nop 1
	v_permlane16_swap_b32_e32 v235, v202
	v_add_f32_e32 v235, v235, v202
	v_mov_b32_e32 v236, v235
	s_nop 1
	v_permlane32_swap_b32_e32 v235, v236
	s_and_saveexec_b64 s[86:87], s[8:9]
	s_cbranch_execz .LBB0_220
	v_add_f32_e32 v202, v235, v236
	ds_write_b32 v199, v202 offset:64
.LBB0_220:
	s_or_b64 exec, exec, s[86:87]
	ds_read_b32 v202, v210
	s_waitcnt lgkmcnt(0)
	v_sub_f32_e32 v235, v124, v202
	v_sub_f32_e32 v236, v125, v202
	v_mul_f32_e32 v235, 0x3fb8aa3b, v235
	v_sub_f32_e32 v237, v126, v202
	v_mul_f32_e32 v236, 0x3fb8aa3b, v236
	v_exp_f32_e32 v235, v235
	v_exp_f32_e32 v236, v236
	v_mul_f32_e32 v237, 0x3fb8aa3b, v237
	v_sub_f32_e32 v238, v127, v202
	v_exp_f32_e32 v237, v237
	v_mul_f32_e32 v238, 0x3fb8aa3b, v238
	v_sub_f32_e32 v239, v120, v202
	v_exp_f32_e32 v238, v238
	v_mul_f32_e32 v239, 0x3fb8aa3b, v239
	v_sub_f32_e32 v240, v121, v202
	v_cndmask_b32_e64 v235, v235, 0, s[50:51]
	v_exp_f32_e32 v239, v239
	v_mul_f32_e32 v240, 0x3fb8aa3b, v240
	v_sub_f32_e32 v241, v122, v202
	v_cndmask_b32_e64 v236, 0, v236, s[52:53]
	v_fma_f32 v243, v104, v235, 0
	v_exp_f32_e32 v240, v240
	v_mul_f32_e32 v241, 0x3fb8aa3b, v241
	v_sub_f32_e32 v202, v123, v202
	v_fmac_f32_e32 v243, v105, v236
	v_cndmask_b32_e64 v237, v237, 0, s[54:55]
	v_exp_f32_e32 v241, v241
	v_mul_f32_e32 v202, 0x3fb8aa3b, v202
	v_fmac_f32_e32 v243, v106, v237
	v_cndmask_b32_e64 v238, v238, 0, s[56:57]
	v_exp_f32_e32 v202, v202
	v_fmac_f32_e32 v243, v107, v238
	v_cndmask_b32_e64 v239, v239, 0, s[58:59]
	v_fmac_f32_e32 v243, v92, v239
	v_cndmask_b32_e64 v240, v240, 0, s[60:61]
	v_fmac_f32_e32 v243, v93, v240
	v_cndmask_b32_e64 v241, v241, 0, s[62:63]
	v_fmac_f32_e32 v243, v94, v241
	v_cndmask_b32_e64 v242, v202, 0, s[64:65]
	v_fmac_f32_e32 v243, v95, v242
	v_mov_b32_e32 v202, v243
	s_nop 1
	v_permlane16_swap_b32_e32 v243, v202
	v_add_f32_e32 v243, v243, v202
	v_mov_b32_e32 v244, v243
	s_nop 1
	v_permlane32_swap_b32_e32 v243, v244
	s_and_saveexec_b64 s[86:87], s[8:9]
	s_cbranch_execz .LBB0_222
	v_add_f32_e32 v202, v243, v244
	ds_write_b32 v199, v202 offset:128
.LBB0_222:
	s_or_b64 exec, exec, s[86:87]
	ds_read_b32 v202, v211
	s_waitcnt lgkmcnt(0)
	v_sub_f32_e32 v124, v124, v202
	v_sub_f32_e32 v125, v125, v202
	v_mul_f32_e32 v124, 0x3fb8aa3b, v124
	v_sub_f32_e32 v126, v126, v202
	v_mul_f32_e32 v125, 0x3fb8aa3b, v125
	v_exp_f32_e32 v124, v124
	v_exp_f32_e32 v125, v125
	v_mul_f32_e32 v126, 0x3fb8aa3b, v126
	v_sub_f32_e32 v127, v127, v202
	v_exp_f32_e32 v126, v126
	v_mul_f32_e32 v127, 0x3fb8aa3b, v127
	v_sub_f32_e32 v120, v120, v202
	v_exp_f32_e32 v127, v127
	v_mul_f32_e32 v120, 0x3fb8aa3b, v120
	v_sub_f32_e32 v121, v121, v202
	v_cndmask_b32_e64 v124, v124, 0, s[66:67]
	v_exp_f32_e32 v120, v120
	v_mul_f32_e32 v121, 0x3fb8aa3b, v121
	v_sub_f32_e32 v122, v122, v202
	v_cndmask_b32_e64 v125, 0, v125, s[68:69]
	v_fma_f32 v243, v96, v124, 0
	v_exp_f32_e32 v121, v121
	v_mul_f32_e32 v122, 0x3fb8aa3b, v122
	v_sub_f32_e32 v123, v123, v202
	v_fmac_f32_e32 v243, v97, v125
	v_cndmask_b32_e64 v126, v126, 0, s[70:71]
	v_exp_f32_e32 v122, v122
	v_mul_f32_e32 v123, 0x3fb8aa3b, v123
	v_fmac_f32_e32 v243, v98, v126
	v_cndmask_b32_e64 v127, v127, 0, s[72:73]
	v_exp_f32_e32 v123, v123
	v_fmac_f32_e32 v243, v99, v127
	v_cndmask_b32_e64 v120, v120, 0, s[74:75]
	v_fmac_f32_e32 v243, v88, v120
	v_cndmask_b32_e64 v121, v121, 0, s[76:77]
	v_fmac_f32_e32 v243, v89, v121
	v_cndmask_b32_e64 v122, v122, 0, s[78:79]
	v_fmac_f32_e32 v243, v90, v122
	v_cndmask_b32_e64 v123, v123, 0, s[80:81]
	v_fmac_f32_e32 v243, v91, v123
	v_mov_b32_e32 v202, v243
	s_nop 1
	v_permlane16_swap_b32_e32 v243, v202
	v_add_f32_e32 v243, v243, v202
	v_mov_b32_e32 v244, v243
	s_nop 1
	v_permlane32_swap_b32_e32 v243, v244
	s_and_saveexec_b64 s[86:87], s[8:9]
	s_cbranch_execz .LBB0_224
	v_add_f32_e32 v202, v243, v244
	ds_write_b32 v199, v202 offset:192
